# deferred weight conversions in phase 3 rebalanced: workgroups without chunk work take a 3.5x share
# speedup vs baseline: 1.0588x; 1.0088x over previous
; #define LAS __attribute__((address_space(3)))
; __device__ __forceinline__ unsigned pk2(float lo, float hi) { const f32x2_t v = {lo, hi}; const bf16x2_t b = __builtin_convertvector(v, bf16x2_t); return __builtin_bit_cast(unsigned, b); }
; #define LDS_WAIT() asm volatile("s_waitcnt lgkmcnt(0)" ::: "memory")
; __device__ __forceinline__ void transpose_item(const float* W, int N, int K, bf16_t* WT, int k0, int n0src, int n0dst, LAS float* scr, int lane) {
;     float tv[32];
; #pragma unroll
;     for (int i = 0; i < 32; ++i) tv[i] = __builtin_nontemporal_load(&W[(size_t)(k0 + 2 * i + (lane >> 5)) * N + n0src + (lane & 31)]);
; #pragma unroll
;     for (int i = 0; i < 32; ++i) scr[(2 * i + (lane >> 5)) * 33 + (lane & 31)] = tv[i];
;     LDS_WAIT();
;     const int c = lane & 7;
; #pragma unroll
;     for (int j = 0; j < 4; ++j) { const int n = (lane >> 3) + 8 * j; const LAS float* s = scr + (8 * c) * 33 + n;
;         u32x4 o; o.x = pk2(s[0 * 33], s[1 * 33]); o.y = pk2(s[2 * 33], s[3 * 33]); o.z = pk2(s[4 * 33], s[5 * 33]); o.w = pk2(s[6 * 33], s[7 * 33]);
;         *(u32x4*)(WT + (size_t)(n0dst + n) * K + k0 + 8 * c) = o; }
;     LDS_WAIT();
; }
; __device__ __forceinline__ void convert_items(const Params& p, LAS float* scr, int lane, int gw, int NGW, int it_lo, int it_hi) {
;     ...
;         if (r < CV_GATE) { const int kb = r / 352, nb = r % 352, ns = nb * 32; int nd; if (ns < DFF) nd = 256 * (ns / 128) + (ns % 128); else { const int j = ns - DFF; nd = 256 * (j / 128) + 128 + (j % 128); }
;             transpose_item(p.in[19], 2 * DFF, 2048, (bf16_t*)(ws + WS_WGATE), kb * 64, ns, nd, scr, lane); continue; } r -= CV_GATE;
.LBB0_896:
	s_or_b64 exec, exec, s[0:1]
	s_mov_b64 exec, -1
	v_mbcnt_lo_u32_b32 v0, -1, 0
	v_mbcnt_hi_u32_b32 v0, -1, v0
	s_lshr_b32 s84, s24, 6
	s_cmp_gt_u32 s2, 0xbf
	s_cbranch_scc1 .Lgconv_gate_hi
	s_sub_i32 s85, s2, 64
	s_lshl_b32 s85, s85, 3
	s_add_i32 s85, s85, s84
	s_mul_i32 s88, s85, 2
	s_add_i32 s89, s88, 2
	s_branch .Lgconv_gate_slots
.Lgconv_gate_hi:
	s_sub_i32 s85, s2, 0xc0
	s_lshl_b32 s85, s85, 3
	s_add_i32 s85, s85, s84
	s_mul_i32 s88, s85, 7
	s_add_i32 s88, s88, 0x800
	s_add_i32 s89, s88, 7
.Lgconv_gate_slots:
	s_add_i32 s85, s88, 0x0
	s_sub_i32 s91, s85, 0x1600
	s_cmp_ge_u32 s85, 0x1600
	s_cselect_b32 s85, s91, s85
	v_readlane_b32 s86, v254, 6
	v_readlane_b32 s87, v254, 7
	s_mul_i32 s90, s84, 0x2100
	v_lshrrev_b32_e32 v1, 5, v0
	v_and_b32_e32 v2, 31, v0
	v_mul_u32_u24_e32 v3, 0xb000, v1
	v_lshl_add_u32 v3, v2, 2, v3
	v_mul_u32_u24_e32 v4, 33, v1
	v_add_u32_e32 v4, v4, v2
	v_lshl_add_u32 v4, v4, 2, s90
	v_and_b32_e32 v5, 7, v0
	v_lshrrev_b32_e32 v6, 3, v0
	v_mul_u32_u24_e32 v7, 0x420, v5
	v_lshl_add_u32 v7, v6, 2, v7
	v_add_u32_e32 v7, s90, v7
	v_mul_u32_u24_e32 v8, 0x1000, v6
	v_lshl_add_u32 v8, v5, 4, v8
	v_add_u32_e32 v9, 0x8000, v8
	v_add_u32_e32 v10, 0x10000, v8
	v_add_u32_e32 v11, 0x18000, v8
.Lgconv_gate_loop:
	s_cmp_lt_u32 s85, 0x2c00
	s_cbranch_scc0 .Lgconv_gate_next
	s_mul_i32 s91, s85, 0xba2f
	s_lshr_b32 s91, s91, 24
	s_mul_i32 s92, s91, 0x160
	s_sub_i32 s92, s85, s92
	s_lshl_b32 s92, s92, 5
	s_cmp_lt_u32 s92, 0x1600
	s_cselect_b32 s93, 0, 0x1600
	s_cselect_b32 s94, 0, 0x80
	s_sub_i32 s93, s92, s93
	s_lshr_b32 s95, s93, 7
	s_lshl_b32 s95, s95, 8
	s_and_b32 s93, s93, 0x7f
	s_add_i32 s95, s95, s93
	s_add_i32 s95, s95, s94
	s_mul_i32 s96, s91, 0x2c0000
	s_lshl_b32 s97, s92, 2
	s_add_i32 s96, s96, s97
	s_add_u32 s96, s86, s96
	s_addc_u32 s97, s87, 0
	global_load_dword v16, v3, s[96:97] nt
	s_add_u32 s96, s96, 0x16000
	s_addc_u32 s97, s97, 0
	global_load_dword v17, v3, s[96:97] nt
	s_add_u32 s96, s96, 0x16000
	s_addc_u32 s97, s97, 0
	global_load_dword v18, v3, s[96:97] nt
	s_add_u32 s96, s96, 0x16000
	s_addc_u32 s97, s97, 0
	global_load_dword v19, v3, s[96:97] nt
	s_add_u32 s96, s96, 0x16000
	s_addc_u32 s97, s97, 0
	global_load_dword v20, v3, s[96:97] nt
	s_add_u32 s96, s96, 0x16000
	s_addc_u32 s97, s97, 0
	global_load_dword v21, v3, s[96:97] nt
	s_add_u32 s96, s96, 0x16000
	s_addc_u32 s97, s97, 0
	global_load_dword v22, v3, s[96:97] nt
	s_add_u32 s96, s96, 0x16000
	s_addc_u32 s97, s97, 0
	global_load_dword v23, v3, s[96:97] nt
	s_add_u32 s96, s96, 0x16000
	s_addc_u32 s97, s97, 0
	global_load_dword v24, v3, s[96:97] nt
	s_add_u32 s96, s96, 0x16000
	s_addc_u32 s97, s97, 0
	global_load_dword v25, v3, s[96:97] nt
	s_add_u32 s96, s96, 0x16000
	s_addc_u32 s97, s97, 0
	global_load_dword v26, v3, s[96:97] nt
	s_add_u32 s96, s96, 0x16000
	s_addc_u32 s97, s97, 0
	global_load_dword v27, v3, s[96:97] nt
	s_add_u32 s96, s96, 0x16000
	s_addc_u32 s97, s97, 0
	global_load_dword v28, v3, s[96:97] nt
	s_add_u32 s96, s96, 0x16000
	s_addc_u32 s97, s97, 0
	global_load_dword v29, v3, s[96:97] nt
	s_add_u32 s96, s96, 0x16000
	s_addc_u32 s97, s97, 0
	global_load_dword v30, v3, s[96:97] nt
	s_add_u32 s96, s96, 0x16000
	s_addc_u32 s97, s97, 0
	global_load_dword v31, v3, s[96:97] nt
	s_add_u32 s96, s96, 0x16000
	s_addc_u32 s97, s97, 0
	global_load_dword v32, v3, s[96:97] nt
	s_add_u32 s96, s96, 0x16000
	s_addc_u32 s97, s97, 0
	global_load_dword v33, v3, s[96:97] nt
	s_add_u32 s96, s96, 0x16000
	s_addc_u32 s97, s97, 0
	global_load_dword v34, v3, s[96:97] nt
	s_add_u32 s96, s96, 0x16000
	s_addc_u32 s97, s97, 0
	global_load_dword v35, v3, s[96:97] nt
	s_add_u32 s96, s96, 0x16000
	s_addc_u32 s97, s97, 0
	global_load_dword v36, v3, s[96:97] nt
	s_add_u32 s96, s96, 0x16000
	s_addc_u32 s97, s97, 0
	global_load_dword v37, v3, s[96:97] nt
	s_add_u32 s96, s96, 0x16000
	s_addc_u32 s97, s97, 0
	global_load_dword v38, v3, s[96:97] nt
	s_add_u32 s96, s96, 0x16000
	s_addc_u32 s97, s97, 0
	global_load_dword v39, v3, s[96:97] nt
	s_add_u32 s96, s96, 0x16000
	s_addc_u32 s97, s97, 0
	global_load_dword v40, v3, s[96:97] nt
	s_add_u32 s96, s96, 0x16000
	s_addc_u32 s97, s97, 0
	global_load_dword v41, v3, s[96:97] nt
	s_add_u32 s96, s96, 0x16000
	s_addc_u32 s97, s97, 0
	global_load_dword v42, v3, s[96:97] nt
	s_add_u32 s96, s96, 0x16000
	s_addc_u32 s97, s97, 0
	global_load_dword v43, v3, s[96:97] nt
	s_add_u32 s96, s96, 0x16000
	s_addc_u32 s97, s97, 0
	global_load_dword v44, v3, s[96:97] nt
	s_add_u32 s96, s96, 0x16000
	s_addc_u32 s97, s97, 0
	global_load_dword v45, v3, s[96:97] nt
	s_add_u32 s96, s96, 0x16000
	s_addc_u32 s97, s97, 0
	global_load_dword v46, v3, s[96:97] nt
	s_add_u32 s96, s96, 0x16000
	s_addc_u32 s97, s97, 0
	global_load_dword v47, v3, s[96:97] nt
	s_mul_i32 s92, s95, 0x1000
	s_lshl_b32 s93, s91, 7
	s_add_i32 s92, s92, s93
	s_add_u32 s92, s22, s92
	s_addc_u32 s93, s23, 0
	s_add_u32 s92, s92, 0x1480000
	s_addc_u32 s93, s93, 0
	s_waitcnt vmcnt(31)
; #define LAS __attribute__((address_space(3)))
; __device__ __forceinline__ unsigned pk2(float lo, float hi) { const f32x2_t v = {lo, hi}; const bf16x2_t b = __builtin_convertvector(v, bf16x2_t); return __builtin_bit_cast(unsigned, b); }
; #define LDS_WAIT() asm volatile("s_waitcnt lgkmcnt(0)" ::: "memory")
; __device__ __forceinline__ void transpose_item(const float* W, int N, int K, bf16_t* WT, int k0, int n0src, int n0dst, LAS float* scr, int lane) {
;     ...
;     for (int i = 0; i < 32; ++i) scr[(2 * i + (lane >> 5)) * 33 + (lane & 31)] = tv[i];
;     LDS_WAIT();
;     const int c = lane & 7;
; #pragma unroll
;     for (int j = 0; j < 4; ++j) { const int n = (lane >> 3) + 8 * j; const LAS float* s = scr + (8 * c) * 33 + n;
;         u32x4 o; o.x = pk2(s[0 * 33], s[1 * 33]); o.y = pk2(s[2 * 33], s[3 * 33]); o.z = pk2(s[4 * 33], s[5 * 33]); o.w = pk2(s[6 * 33], s[7 * 33]);
;         *(u32x4*)(WT + (size_t)(n0dst + n) * K + k0 + 8 * c) = o; }
;     LDS_WAIT();
; }
; __device__ __forceinline__ void convert_items(const Params& p, LAS float* scr, int lane, int gw, int NGW, int it_lo, int it_hi) {
;     ...
;         if (r < CV_2K) { const int kb = r / 64, nb = r % 64; transpose_item(p.in[17], 2048, 2048, (bf16_t*)(ws + WS_WO), kb * 64, nb * 32, nb * 32, scr, lane); continue; } r -= CV_2K;
	ds_write_b32 v4, v16
	s_waitcnt vmcnt(30)
	ds_write_b32 v4, v17 offset:264
	s_waitcnt vmcnt(29)
	ds_write_b32 v4, v18 offset:528
	s_waitcnt vmcnt(28)
	ds_write_b32 v4, v19 offset:792
	s_waitcnt vmcnt(27)
	ds_write_b32 v4, v20 offset:1056
	s_waitcnt vmcnt(26)
	ds_write_b32 v4, v21 offset:1320
	s_waitcnt vmcnt(25)
	ds_write_b32 v4, v22 offset:1584
	s_waitcnt vmcnt(24)
	ds_write_b32 v4, v23 offset:1848
	s_waitcnt vmcnt(23)
	ds_write_b32 v4, v24 offset:2112
	s_waitcnt vmcnt(22)
	ds_write_b32 v4, v25 offset:2376
	s_waitcnt vmcnt(21)
	ds_write_b32 v4, v26 offset:2640
	s_waitcnt vmcnt(20)
	ds_write_b32 v4, v27 offset:2904
	s_waitcnt vmcnt(19)
	ds_write_b32 v4, v28 offset:3168
	s_waitcnt vmcnt(18)
	ds_write_b32 v4, v29 offset:3432
	s_waitcnt vmcnt(17)
	ds_write_b32 v4, v30 offset:3696
	s_waitcnt vmcnt(16)
	ds_write_b32 v4, v31 offset:3960
	s_waitcnt vmcnt(15)
	ds_write_b32 v4, v32 offset:4224
	s_waitcnt vmcnt(14)
	ds_write_b32 v4, v33 offset:4488
	s_waitcnt vmcnt(13)
	ds_write_b32 v4, v34 offset:4752
	s_waitcnt vmcnt(12)
	ds_write_b32 v4, v35 offset:5016
	s_waitcnt vmcnt(11)
	ds_write_b32 v4, v36 offset:5280
	s_waitcnt vmcnt(10)
	ds_write_b32 v4, v37 offset:5544
	s_waitcnt vmcnt(9)
	ds_write_b32 v4, v38 offset:5808
	s_waitcnt vmcnt(8)
	ds_write_b32 v4, v39 offset:6072
	s_waitcnt vmcnt(7)
	ds_write_b32 v4, v40 offset:6336
	s_waitcnt vmcnt(6)
	ds_write_b32 v4, v41 offset:6600
	s_waitcnt vmcnt(5)
	ds_write_b32 v4, v42 offset:6864
	s_waitcnt vmcnt(4)
	ds_write_b32 v4, v43 offset:7128
	s_waitcnt vmcnt(3)
	ds_write_b32 v4, v44 offset:7392
	s_waitcnt vmcnt(2)
	ds_write_b32 v4, v45 offset:7656
	s_waitcnt vmcnt(1)
	ds_write_b32 v4, v46 offset:7920
	s_waitcnt vmcnt(0)
	ds_write_b32 v4, v47 offset:8184
	s_waitcnt lgkmcnt(0)
	ds_read_b32 v48, v7
	ds_read_b32 v49, v7 offset:132
	ds_read_b32 v50, v7 offset:264
	ds_read_b32 v51, v7 offset:396
	ds_read_b32 v52, v7 offset:528
	ds_read_b32 v53, v7 offset:660
	ds_read_b32 v54, v7 offset:792
	ds_read_b32 v55, v7 offset:924
	s_waitcnt lgkmcnt(0)
	v_cvt_pk_bf16_f32 v80, v48, v49
	v_cvt_pk_bf16_f32 v81, v50, v51
	v_cvt_pk_bf16_f32 v82, v52, v53
	v_cvt_pk_bf16_f32 v83, v54, v55
	global_store_dwordx4 v8, v[80:83], s[92:93]
	ds_read_b32 v56, v7 offset:32
	ds_read_b32 v57, v7 offset:164
	ds_read_b32 v58, v7 offset:296
	ds_read_b32 v59, v7 offset:428
	ds_read_b32 v60, v7 offset:560
	ds_read_b32 v61, v7 offset:692
	ds_read_b32 v62, v7 offset:824
	ds_read_b32 v63, v7 offset:956
	s_waitcnt lgkmcnt(0)
	v_cvt_pk_bf16_f32 v84, v56, v57
	v_cvt_pk_bf16_f32 v85, v58, v59
	v_cvt_pk_bf16_f32 v86, v60, v61
	v_cvt_pk_bf16_f32 v87, v62, v63
	global_store_dwordx4 v9, v[84:87], s[92:93]
	ds_read_b32 v64, v7 offset:64
	ds_read_b32 v65, v7 offset:196
	ds_read_b32 v66, v7 offset:328
	ds_read_b32 v67, v7 offset:460
	ds_read_b32 v68, v7 offset:592
	ds_read_b32 v69, v7 offset:724
	ds_read_b32 v70, v7 offset:856
	ds_read_b32 v71, v7 offset:988
	s_waitcnt lgkmcnt(0)
	v_cvt_pk_bf16_f32 v88, v64, v65
	v_cvt_pk_bf16_f32 v89, v66, v67
	v_cvt_pk_bf16_f32 v90, v68, v69
	v_cvt_pk_bf16_f32 v91, v70, v71
	global_store_dwordx4 v10, v[88:91], s[92:93]
	ds_read_b32 v72, v7 offset:96
	ds_read_b32 v73, v7 offset:228
	ds_read_b32 v74, v7 offset:360
	ds_read_b32 v75, v7 offset:492
	ds_read_b32 v76, v7 offset:624
	ds_read_b32 v77, v7 offset:756
	ds_read_b32 v78, v7 offset:888
	ds_read_b32 v79, v7 offset:1020
	s_waitcnt lgkmcnt(0)
	v_cvt_pk_bf16_f32 v92, v72, v73
	v_cvt_pk_bf16_f32 v93, v74, v75
	v_cvt_pk_bf16_f32 v94, v76, v77
	v_cvt_pk_bf16_f32 v95, v78, v79
	global_store_dwordx4 v11, v[92:95], s[92:93]
	s_add_i32 s85, s85, 0x1600
	s_branch .Lgconv_gate_loop
.Lgconv_gate_next:
	s_add_i32 s88, s88, 1
	s_cmp_lt_u32 s88, s89
	s_cbranch_scc0 .Lgconv_gate_done
	s_branch .Lgconv_gate_slots
.Lgconv_gate_done:
	s_mov_b64 exec, -1
	v_mbcnt_lo_u32_b32 v0, -1, 0
	v_mbcnt_hi_u32_b32 v0, -1, v0
	s_lshr_b32 s84, s24, 6
	s_cmp_gt_u32 s2, 0xbf
	s_cbranch_scc1 .Lgconv_wo_hi
	s_sub_i32 s85, s2, 64
	s_lshl_b32 s85, s85, 3
	s_add_i32 s85, s85, s84
	s_mul_i32 s88, s85, 2
	s_add_i32 s89, s88, 2
	s_branch .Lgconv_wo_slots

; #define LAS __attribute__((address_space(3)))
; __device__ __forceinline__ void transpose_item(const float* W, int N, int K, bf16_t* WT, int k0, int n0src, int n0dst, LAS float* scr, int lane) {
;     float tv[32];
; #pragma unroll
;     for (int i = 0; i < 32; ++i) tv[i] = __builtin_nontemporal_load(&W[(size_t)(k0 + 2 * i + (lane >> 5)) * N + n0src + (lane & 31)]);
; #pragma unroll
; __device__ __forceinline__ void convert_items(const Params& p, LAS float* scr, int lane, int gw, int NGW, int it_lo, int it_hi) {
;     ...
;         if (r < CV_2K) { const int kb = r / 64, nb = r % 64; transpose_item(p.in[17], 2048, 2048, (bf16_t*)(ws + WS_WO), kb * 64, nb * 32, nb * 32, scr, lane); continue; } r -= CV_2K;
.Lgconv_wo_slots:
	s_add_i32 s85, s88, 0xe00
	s_sub_i32 s91, s85, 0x1600
	s_cmp_ge_u32 s85, 0x1600
	s_cselect_b32 s85, s91, s85
	v_readlane_b32 s86, v254, 2
	v_readlane_b32 s87, v254, 3
	s_mul_i32 s90, s84, 0x2100
	v_lshrrev_b32_e32 v1, 5, v0
	v_and_b32_e32 v2, 31, v0
	v_mul_u32_u24_e32 v3, 0x2000, v1
	v_lshl_add_u32 v3, v2, 2, v3
	v_mul_u32_u24_e32 v4, 33, v1
	v_add_u32_e32 v4, v4, v2
	v_lshl_add_u32 v4, v4, 2, s90
	v_and_b32_e32 v5, 7, v0
	v_lshrrev_b32_e32 v6, 3, v0
	v_mul_u32_u24_e32 v7, 0x420, v5
	v_lshl_add_u32 v7, v6, 2, v7
	v_add_u32_e32 v7, s90, v7
	v_mul_u32_u24_e32 v8, 0x1000, v6
	v_lshl_add_u32 v8, v5, 4, v8
	v_add_u32_e32 v9, 0x8000, v8
	v_add_u32_e32 v10, 0x10000, v8
	v_add_u32_e32 v11, 0x18000, v8
; #define LAS __attribute__((address_space(3)))
; __device__ __forceinline__ unsigned pk2(float lo, float hi) { const f32x2_t v = {lo, hi}; const bf16x2_t b = __builtin_convertvector(v, bf16x2_t); return __builtin_bit_cast(unsigned, b); }
; #define LDS_WAIT() asm volatile("s_waitcnt lgkmcnt(0)" ::: "memory")
; __device__ __forceinline__ void transpose_item(const float* W, int N, int K, bf16_t* WT, int k0, int n0src, int n0dst, LAS float* scr, int lane) {
;     float tv[32];
; #pragma unroll
;     for (int i = 0; i < 32; ++i) tv[i] = __builtin_nontemporal_load(&W[(size_t)(k0 + 2 * i + (lane >> 5)) * N + n0src + (lane & 31)]);
; #pragma unroll
;     for (int i = 0; i < 32; ++i) scr[(2 * i + (lane >> 5)) * 33 + (lane & 31)] = tv[i];
;     LDS_WAIT();
;     const int c = lane & 7;
; #pragma unroll
;     for (int j = 0; j < 4; ++j) { const int n = (lane >> 3) + 8 * j; const LAS float* s = scr + (8 * c) * 33 + n;
;         u32x4 o; o.x = pk2(s[0 * 33], s[1 * 33]); o.y = pk2(s[2 * 33], s[3 * 33]); o.z = pk2(s[4 * 33], s[5 * 33]); o.w = pk2(s[6 * 33], s[7 * 33]);
;         *(u32x4*)(WT + (size_t)(n0dst + n) * K + k0 + 8 * c) = o; }
;     LDS_WAIT();
; }
; __device__ __forceinline__ void convert_items(const Params& p, LAS float* scr, int lane, int gw, int NGW, int it_lo, int it_hi) {
;     ...
;         if (r < CV_2K) { const int kb = r / 64, nb = r % 64; transpose_item(p.in[17], 2048, 2048, (bf16_t*)(ws + WS_WO), kb * 64, nb * 32, nb * 32, scr, lane); continue; } r -= CV_2K;
.Lgconv_wo_loop:
	s_cmp_lt_u32 s85, 0x800
	s_cbranch_scc0 .Lgconv_wo_next
	s_lshr_b32 s91, s85, 6
	s_mul_i32 s92, s91, 0x40
	s_sub_i32 s92, s85, s92
	s_lshl_b32 s92, s92, 5
	s_mov_b32 s95, s92
	s_mul_i32 s96, s91, 0x80000
	s_lshl_b32 s97, s92, 2
	s_add_i32 s96, s96, s97
	s_add_u32 s96, s86, s96
	s_addc_u32 s97, s87, 0
	global_load_dword v16, v3, s[96:97] nt
	s_add_u32 s96, s96, 0x4000
	s_addc_u32 s97, s97, 0
	global_load_dword v17, v3, s[96:97] nt
	s_add_u32 s96, s96, 0x4000
	s_addc_u32 s97, s97, 0
	global_load_dword v18, v3, s[96:97] nt
	s_add_u32 s96, s96, 0x4000
	s_addc_u32 s97, s97, 0
	global_load_dword v19, v3, s[96:97] nt
	s_add_u32 s96, s96, 0x4000
	s_addc_u32 s97, s97, 0
	global_load_dword v20, v3, s[96:97] nt
	s_add_u32 s96, s96, 0x4000
	s_addc_u32 s97, s97, 0
	global_load_dword v21, v3, s[96:97] nt
	s_add_u32 s96, s96, 0x4000
	s_addc_u32 s97, s97, 0
	global_load_dword v22, v3, s[96:97] nt
	s_add_u32 s96, s96, 0x4000
	s_addc_u32 s97, s97, 0
	global_load_dword v23, v3, s[96:97] nt
	s_add_u32 s96, s96, 0x4000
	s_addc_u32 s97, s97, 0
	global_load_dword v24, v3, s[96:97] nt
	s_add_u32 s96, s96, 0x4000
	s_addc_u32 s97, s97, 0
	global_load_dword v25, v3, s[96:97] nt
	s_add_u32 s96, s96, 0x4000
	s_addc_u32 s97, s97, 0
	global_load_dword v26, v3, s[96:97] nt
	s_add_u32 s96, s96, 0x4000
	s_addc_u32 s97, s97, 0
	global_load_dword v27, v3, s[96:97] nt
	s_add_u32 s96, s96, 0x4000
	s_addc_u32 s97, s97, 0
	global_load_dword v28, v3, s[96:97] nt
	s_add_u32 s96, s96, 0x4000
	s_addc_u32 s97, s97, 0
	global_load_dword v29, v3, s[96:97] nt
	s_add_u32 s96, s96, 0x4000
	s_addc_u32 s97, s97, 0
	global_load_dword v30, v3, s[96:97] nt
	s_add_u32 s96, s96, 0x4000
	s_addc_u32 s97, s97, 0
	global_load_dword v31, v3, s[96:97] nt
	s_add_u32 s96, s96, 0x4000
	s_addc_u32 s97, s97, 0
	global_load_dword v32, v3, s[96:97] nt
	s_add_u32 s96, s96, 0x4000
	s_addc_u32 s97, s97, 0
	global_load_dword v33, v3, s[96:97] nt
	s_add_u32 s96, s96, 0x4000
	s_addc_u32 s97, s97, 0
	global_load_dword v34, v3, s[96:97] nt
	s_add_u32 s96, s96, 0x4000
	s_addc_u32 s97, s97, 0
	global_load_dword v35, v3, s[96:97] nt
	s_add_u32 s96, s96, 0x4000
	s_addc_u32 s97, s97, 0
	global_load_dword v36, v3, s[96:97] nt
	s_add_u32 s96, s96, 0x4000
	s_addc_u32 s97, s97, 0
	global_load_dword v37, v3, s[96:97] nt
	s_add_u32 s96, s96, 0x4000
	s_addc_u32 s97, s97, 0
	global_load_dword v38, v3, s[96:97] nt
	s_add_u32 s96, s96, 0x4000
	s_addc_u32 s97, s97, 0
	global_load_dword v39, v3, s[96:97] nt
	s_add_u32 s96, s96, 0x4000
	s_addc_u32 s97, s97, 0
	global_load_dword v40, v3, s[96:97] nt
	s_add_u32 s96, s96, 0x4000
	s_addc_u32 s97, s97, 0
	global_load_dword v41, v3, s[96:97] nt
	s_add_u32 s96, s96, 0x4000
	s_addc_u32 s97, s97, 0
	global_load_dword v42, v3, s[96:97] nt
	s_add_u32 s96, s96, 0x4000
	s_addc_u32 s97, s97, 0
	global_load_dword v43, v3, s[96:97] nt
	s_add_u32 s96, s96, 0x4000
	s_addc_u32 s97, s97, 0
	global_load_dword v44, v3, s[96:97] nt
	s_add_u32 s96, s96, 0x4000
	s_addc_u32 s97, s97, 0
	global_load_dword v45, v3, s[96:97] nt
	s_add_u32 s96, s96, 0x4000
	s_addc_u32 s97, s97, 0
	global_load_dword v46, v3, s[96:97] nt
	s_add_u32 s96, s96, 0x4000
	s_addc_u32 s97, s97, 0
	global_load_dword v47, v3, s[96:97] nt
	s_mul_i32 s92, s95, 0x1000
	s_lshl_b32 s93, s91, 7
	s_add_i32 s92, s92, s93
	s_add_u32 s92, s22, s92
	s_addc_u32 s93, s23, 0
	s_add_u32 s92, s92, 0xc80000
	s_addc_u32 s93, s93, 0
	s_waitcnt vmcnt(31)
	ds_write_b32 v4, v16
	s_waitcnt vmcnt(30)
	ds_write_b32 v4, v17 offset:264
	s_waitcnt vmcnt(29)
	ds_write_b32 v4, v18 offset:528
	s_waitcnt vmcnt(28)
	ds_write_b32 v4, v19 offset:792
	s_waitcnt vmcnt(27)
	ds_write_b32 v4, v20 offset:1056
	s_waitcnt vmcnt(26)
	ds_write_b32 v4, v21 offset:1320
	s_waitcnt vmcnt(25)
	ds_write_b32 v4, v22 offset:1584
	s_waitcnt vmcnt(24)
	ds_write_b32 v4, v23 offset:1848
	s_waitcnt vmcnt(23)
	ds_write_b32 v4, v24 offset:2112
	s_waitcnt vmcnt(22)
	ds_write_b32 v4, v25 offset:2376
	s_waitcnt vmcnt(21)
	ds_write_b32 v4, v26 offset:2640
	s_waitcnt vmcnt(20)
	ds_write_b32 v4, v27 offset:2904
	s_waitcnt vmcnt(19)
	ds_write_b32 v4, v28 offset:3168
	s_waitcnt vmcnt(18)
	ds_write_b32 v4, v29 offset:3432
	s_waitcnt vmcnt(17)
	ds_write_b32 v4, v30 offset:3696
	s_waitcnt vmcnt(16)
	ds_write_b32 v4, v31 offset:3960
	s_waitcnt vmcnt(15)
	ds_write_b32 v4, v32 offset:4224
	s_waitcnt vmcnt(14)
	ds_write_b32 v4, v33 offset:4488
	s_waitcnt vmcnt(13)
	ds_write_b32 v4, v34 offset:4752
	s_waitcnt vmcnt(12)
	ds_write_b32 v4, v35 offset:5016
	s_waitcnt vmcnt(11)
	ds_write_b32 v4, v36 offset:5280
	s_waitcnt vmcnt(10)
	ds_write_b32 v4, v37 offset:5544
	s_waitcnt vmcnt(9)
	ds_write_b32 v4, v38 offset:5808
	s_waitcnt vmcnt(8)
	ds_write_b32 v4, v39 offset:6072
	s_waitcnt vmcnt(7)
	ds_write_b32 v4, v40 offset:6336
	s_waitcnt vmcnt(6)
	ds_write_b32 v4, v41 offset:6600
	s_waitcnt vmcnt(5)
	ds_write_b32 v4, v42 offset:6864
	s_waitcnt vmcnt(4)
	ds_write_b32 v4, v43 offset:7128
	s_waitcnt vmcnt(3)
	ds_write_b32 v4, v44 offset:7392
	s_waitcnt vmcnt(2)
	ds_write_b32 v4, v45 offset:7656
	s_waitcnt vmcnt(1)
	ds_write_b32 v4, v46 offset:7920
	s_waitcnt vmcnt(0)
	ds_write_b32 v4, v47 offset:8184
	s_waitcnt lgkmcnt(0)
	ds_read_b32 v48, v7
	ds_read_b32 v49, v7 offset:132
	ds_read_b32 v50, v7 offset:264
	ds_read_b32 v51, v7 offset:396
	ds_read_b32 v52, v7 offset:528
	ds_read_b32 v53, v7 offset:660
	ds_read_b32 v54, v7 offset:792
	ds_read_b32 v55, v7 offset:924
	s_waitcnt lgkmcnt(0)
	v_cvt_pk_bf16_f32 v80, v48, v49
	v_cvt_pk_bf16_f32 v81, v50, v51
	v_cvt_pk_bf16_f32 v82, v52, v53
	v_cvt_pk_bf16_f32 v83, v54, v55
	global_store_dwordx4 v8, v[80:83], s[92:93]
	ds_read_b32 v56, v7 offset:32
	ds_read_b32 v57, v7 offset:164
	ds_read_b32 v58, v7 offset:296
	ds_read_b32 v59, v7 offset:428
	ds_read_b32 v60, v7 offset:560
	ds_read_b32 v61, v7 offset:692
	ds_read_b32 v62, v7 offset:824
	ds_read_b32 v63, v7 offset:956
	s_waitcnt lgkmcnt(0)
	v_cvt_pk_bf16_f32 v84, v56, v57
	v_cvt_pk_bf16_f32 v85, v58, v59
	v_cvt_pk_bf16_f32 v86, v60, v61
	v_cvt_pk_bf16_f32 v87, v62, v63
	global_store_dwordx4 v9, v[84:87], s[92:93]
	ds_read_b32 v64, v7 offset:64
	ds_read_b32 v65, v7 offset:196
	ds_read_b32 v66, v7 offset:328
	ds_read_b32 v67, v7 offset:460
	ds_read_b32 v68, v7 offset:592
	ds_read_b32 v69, v7 offset:724
	ds_read_b32 v70, v7 offset:856
	ds_read_b32 v71, v7 offset:988
	s_waitcnt lgkmcnt(0)
	v_cvt_pk_bf16_f32 v88, v64, v65
	v_cvt_pk_bf16_f32 v89, v66, v67
	v_cvt_pk_bf16_f32 v90, v68, v69
	v_cvt_pk_bf16_f32 v91, v70, v71
	global_store_dwordx4 v10, v[88:91], s[92:93]
	ds_read_b32 v72, v7 offset:96
	ds_read_b32 v73, v7 offset:228
	ds_read_b32 v74, v7 offset:360
	ds_read_b32 v75, v7 offset:492
	ds_read_b32 v76, v7 offset:624
	ds_read_b32 v77, v7 offset:756
	ds_read_b32 v78, v7 offset:888
	ds_read_b32 v79, v7 offset:1020
	s_waitcnt lgkmcnt(0)
	v_cvt_pk_bf16_f32 v92, v72, v73
	v_cvt_pk_bf16_f32 v93, v74, v75
	v_cvt_pk_bf16_f32 v94, v76, v77
	v_cvt_pk_bf16_f32 v95, v78, v79
	global_store_dwordx4 v11, v[92:95], s[92:93]
	s_add_i32 s85, s85, 0x1600
	s_branch .Lgconv_wo_loop

; #define LAS __attribute__((address_space(3)))
; __device__ __forceinline__ void transpose_item(const float* W, int N, int K, bf16_t* WT, int k0, int n0src, int n0dst, LAS float* scr, int lane) {
;     float tv[32];
; #pragma unroll
;     for (int i = 0; i < 32; ++i) tv[i] = __builtin_nontemporal_load(&W[(size_t)(k0 + 2 * i + (lane >> 5)) * N + n0src + (lane & 31)]);
; #pragma unroll
; __device__ __forceinline__ void convert_items(const Params& p, LAS float* scr, int lane, int gw, int NGW, int it_lo, int it_hi) {
;     ...
;         if (r < CV_2K) { const int kb = r / 64, nb = r % 64; transpose_item(p.in[16], 2048, 2048, (bf16_t*)(ws + WS_WGU), kb * 64, nb * 32, nb * 32, scr, lane); continue; } r -= CV_2K;
.Lgconv_wgu_slots:
	s_add_i32 s85, s88, 0x600
	s_sub_i32 s91, s85, 0x1600
	s_cmp_ge_u32 s85, 0x1600
	s_cselect_b32 s85, s91, s85
	v_readlane_b32 s86, v254, 0
	v_readlane_b32 s87, v254, 1
	s_mul_i32 s90, s84, 0x2100
	v_lshrrev_b32_e32 v1, 5, v0
	v_and_b32_e32 v2, 31, v0
	v_mul_u32_u24_e32 v3, 0x2000, v1
	v_lshl_add_u32 v3, v2, 2, v3
	v_mul_u32_u24_e32 v4, 33, v1
	v_add_u32_e32 v4, v4, v2
	v_lshl_add_u32 v4, v4, 2, s90
	v_and_b32_e32 v5, 7, v0
	v_lshrrev_b32_e32 v6, 3, v0
	v_mul_u32_u24_e32 v7, 0x420, v5
	v_lshl_add_u32 v7, v6, 2, v7
	v_add_u32_e32 v7, s90, v7
	v_mul_u32_u24_e32 v8, 0x1000, v6
	v_lshl_add_u32 v8, v5, 4, v8
	v_add_u32_e32 v9, 0x8000, v8
	v_add_u32_e32 v10, 0x10000, v8
	v_add_u32_e32 v11, 0x18000, v8
; #define LAS __attribute__((address_space(3)))
; __device__ __forceinline__ unsigned pk2(float lo, float hi) { const f32x2_t v = {lo, hi}; const bf16x2_t b = __builtin_convertvector(v, bf16x2_t); return __builtin_bit_cast(unsigned, b); }
; #define LDS_WAIT() asm volatile("s_waitcnt lgkmcnt(0)" ::: "memory")
; __device__ __forceinline__ void transpose_item(const float* W, int N, int K, bf16_t* WT, int k0, int n0src, int n0dst, LAS float* scr, int lane) {
;     float tv[32];
; #pragma unroll
;     for (int i = 0; i < 32; ++i) tv[i] = __builtin_nontemporal_load(&W[(size_t)(k0 + 2 * i + (lane >> 5)) * N + n0src + (lane & 31)]);
; #pragma unroll
;     for (int i = 0; i < 32; ++i) scr[(2 * i + (lane >> 5)) * 33 + (lane & 31)] = tv[i];
;     LDS_WAIT();
;     const int c = lane & 7;
; #pragma unroll
;     for (int j = 0; j < 4; ++j) { const int n = (lane >> 3) + 8 * j; const LAS float* s = scr + (8 * c) * 33 + n;
;         u32x4 o; o.x = pk2(s[0 * 33], s[1 * 33]); o.y = pk2(s[2 * 33], s[3 * 33]); o.z = pk2(s[4 * 33], s[5 * 33]); o.w = pk2(s[6 * 33], s[7 * 33]);
;         *(u32x4*)(WT + (size_t)(n0dst + n) * K + k0 + 8 * c) = o; }
;     LDS_WAIT();
; }
; __device__ __forceinline__ void convert_items(const Params& p, LAS float* scr, int lane, int gw, int NGW, int it_lo, int it_hi) {
;     ...
;         if (r < CV_2K) { const int kb = r / 64, nb = r % 64; transpose_item(p.in[16], 2048, 2048, (bf16_t*)(ws + WS_WGU), kb * 64, nb * 32, nb * 32, scr, lane); continue; } r -= CV_2K;
.Lgconv_wgu_loop:
	s_cmp_lt_u32 s85, 0x800
	s_cbranch_scc0 .Lgconv_wgu_next
	s_lshr_b32 s91, s85, 6
	s_mul_i32 s92, s91, 0x40
	s_sub_i32 s92, s85, s92
	s_lshl_b32 s92, s92, 5
	s_mov_b32 s95, s92
	s_mul_i32 s96, s91, 0x80000
	s_lshl_b32 s97, s92, 2
	s_add_i32 s96, s96, s97
	s_add_u32 s96, s86, s96
	s_addc_u32 s97, s87, 0
	global_load_dword v16, v3, s[96:97] nt
	s_add_u32 s96, s96, 0x4000
	s_addc_u32 s97, s97, 0
	global_load_dword v17, v3, s[96:97] nt
	s_add_u32 s96, s96, 0x4000
	s_addc_u32 s97, s97, 0
	global_load_dword v18, v3, s[96:97] nt
	s_add_u32 s96, s96, 0x4000
	s_addc_u32 s97, s97, 0
	global_load_dword v19, v3, s[96:97] nt
	s_add_u32 s96, s96, 0x4000
	s_addc_u32 s97, s97, 0
	global_load_dword v20, v3, s[96:97] nt
	s_add_u32 s96, s96, 0x4000
	s_addc_u32 s97, s97, 0
	global_load_dword v21, v3, s[96:97] nt
	s_add_u32 s96, s96, 0x4000
	s_addc_u32 s97, s97, 0
	global_load_dword v22, v3, s[96:97] nt
	s_add_u32 s96, s96, 0x4000
	s_addc_u32 s97, s97, 0
	global_load_dword v23, v3, s[96:97] nt
	s_add_u32 s96, s96, 0x4000
	s_addc_u32 s97, s97, 0
	global_load_dword v24, v3, s[96:97] nt
	s_add_u32 s96, s96, 0x4000
	s_addc_u32 s97, s97, 0
	global_load_dword v25, v3, s[96:97] nt
	s_add_u32 s96, s96, 0x4000
	s_addc_u32 s97, s97, 0
	global_load_dword v26, v3, s[96:97] nt
	s_add_u32 s96, s96, 0x4000
	s_addc_u32 s97, s97, 0
	global_load_dword v27, v3, s[96:97] nt
	s_add_u32 s96, s96, 0x4000
	s_addc_u32 s97, s97, 0
	global_load_dword v28, v3, s[96:97] nt
	s_add_u32 s96, s96, 0x4000
	s_addc_u32 s97, s97, 0
	global_load_dword v29, v3, s[96:97] nt
	s_add_u32 s96, s96, 0x4000
	s_addc_u32 s97, s97, 0
	global_load_dword v30, v3, s[96:97] nt
	s_add_u32 s96, s96, 0x4000
	s_addc_u32 s97, s97, 0
	global_load_dword v31, v3, s[96:97] nt
	s_add_u32 s96, s96, 0x4000
	s_addc_u32 s97, s97, 0
	global_load_dword v32, v3, s[96:97] nt
	s_add_u32 s96, s96, 0x4000
	s_addc_u32 s97, s97, 0
	global_load_dword v33, v3, s[96:97] nt
	s_add_u32 s96, s96, 0x4000
	s_addc_u32 s97, s97, 0
	global_load_dword v34, v3, s[96:97] nt
	s_add_u32 s96, s96, 0x4000
	s_addc_u32 s97, s97, 0
	global_load_dword v35, v3, s[96:97] nt
	s_add_u32 s96, s96, 0x4000
	s_addc_u32 s97, s97, 0
	global_load_dword v36, v3, s[96:97] nt
	s_add_u32 s96, s96, 0x4000
	s_addc_u32 s97, s97, 0
	global_load_dword v37, v3, s[96:97] nt
	s_add_u32 s96, s96, 0x4000
	s_addc_u32 s97, s97, 0
	global_load_dword v38, v3, s[96:97] nt
	s_add_u32 s96, s96, 0x4000
	s_addc_u32 s97, s97, 0
	global_load_dword v39, v3, s[96:97] nt
	s_add_u32 s96, s96, 0x4000
	s_addc_u32 s97, s97, 0
	global_load_dword v40, v3, s[96:97] nt
	s_add_u32 s96, s96, 0x4000
	s_addc_u32 s97, s97, 0
	global_load_dword v41, v3, s[96:97] nt
	s_add_u32 s96, s96, 0x4000
	s_addc_u32 s97, s97, 0
	global_load_dword v42, v3, s[96:97] nt
	s_add_u32 s96, s96, 0x4000
	s_addc_u32 s97, s97, 0
	global_load_dword v43, v3, s[96:97] nt
	s_add_u32 s96, s96, 0x4000
	s_addc_u32 s97, s97, 0
	global_load_dword v44, v3, s[96:97] nt
	s_add_u32 s96, s96, 0x4000
	s_addc_u32 s97, s97, 0
	global_load_dword v45, v3, s[96:97] nt
	s_add_u32 s96, s96, 0x4000
	s_addc_u32 s97, s97, 0
	global_load_dword v46, v3, s[96:97] nt
	s_add_u32 s96, s96, 0x4000
	s_addc_u32 s97, s97, 0
	global_load_dword v47, v3, s[96:97] nt
	s_mul_i32 s92, s95, 0x1000
	s_lshl_b32 s93, s91, 7
	s_add_i32 s92, s92, s93
	s_add_u32 s92, s22, s92
	s_addc_u32 s93, s23, 0
	s_add_u32 s92, s92, 0x480000
	s_addc_u32 s93, s93, 0
	s_waitcnt vmcnt(31)
	ds_write_b32 v4, v16
	s_waitcnt vmcnt(30)
	ds_write_b32 v4, v17 offset:264
	s_waitcnt vmcnt(29)
	ds_write_b32 v4, v18 offset:528
	s_waitcnt vmcnt(28)
	ds_write_b32 v4, v19 offset:792
	s_waitcnt vmcnt(27)
	ds_write_b32 v4, v20 offset:1056
	s_waitcnt vmcnt(26)
	ds_write_b32 v4, v21 offset:1320
	s_waitcnt vmcnt(25)
	ds_write_b32 v4, v22 offset:1584
	s_waitcnt vmcnt(24)
	ds_write_b32 v4, v23 offset:1848
	s_waitcnt vmcnt(23)
	ds_write_b32 v4, v24 offset:2112
	s_waitcnt vmcnt(22)
	ds_write_b32 v4, v25 offset:2376
	s_waitcnt vmcnt(21)
	ds_write_b32 v4, v26 offset:2640
	s_waitcnt vmcnt(20)
	ds_write_b32 v4, v27 offset:2904
	s_waitcnt vmcnt(19)
	ds_write_b32 v4, v28 offset:3168
	s_waitcnt vmcnt(18)
	ds_write_b32 v4, v29 offset:3432
	s_waitcnt vmcnt(17)
	ds_write_b32 v4, v30 offset:3696
	s_waitcnt vmcnt(16)
	ds_write_b32 v4, v31 offset:3960
	s_waitcnt vmcnt(15)
	ds_write_b32 v4, v32 offset:4224
	s_waitcnt vmcnt(14)
	ds_write_b32 v4, v33 offset:4488
	s_waitcnt vmcnt(13)
	ds_write_b32 v4, v34 offset:4752
	s_waitcnt vmcnt(12)
	ds_write_b32 v4, v35 offset:5016
	s_waitcnt vmcnt(11)
	ds_write_b32 v4, v36 offset:5280
	s_waitcnt vmcnt(10)
	ds_write_b32 v4, v37 offset:5544
	s_waitcnt vmcnt(9)
	ds_write_b32 v4, v38 offset:5808
	s_waitcnt vmcnt(8)
	ds_write_b32 v4, v39 offset:6072
	s_waitcnt vmcnt(7)
	ds_write_b32 v4, v40 offset:6336
	s_waitcnt vmcnt(6)
	ds_write_b32 v4, v41 offset:6600
	s_waitcnt vmcnt(5)
	ds_write_b32 v4, v42 offset:6864
	s_waitcnt vmcnt(4)
	ds_write_b32 v4, v43 offset:7128
	s_waitcnt vmcnt(3)
	ds_write_b32 v4, v44 offset:7392
	s_waitcnt vmcnt(2)
	ds_write_b32 v4, v45 offset:7656
	s_waitcnt vmcnt(1)
	ds_write_b32 v4, v46 offset:7920
	s_waitcnt vmcnt(0)
	ds_write_b32 v4, v47 offset:8184
	s_waitcnt lgkmcnt(0)
	ds_read_b32 v48, v7
	ds_read_b32 v49, v7 offset:132
	ds_read_b32 v50, v7 offset:264
	ds_read_b32 v51, v7 offset:396
	ds_read_b32 v52, v7 offset:528
	ds_read_b32 v53, v7 offset:660
	ds_read_b32 v54, v7 offset:792
	ds_read_b32 v55, v7 offset:924
	s_waitcnt lgkmcnt(0)
	v_cvt_pk_bf16_f32 v80, v48, v49
	v_cvt_pk_bf16_f32 v81, v50, v51
	v_cvt_pk_bf16_f32 v82, v52, v53
	v_cvt_pk_bf16_f32 v83, v54, v55
	global_store_dwordx4 v8, v[80:83], s[92:93]
	ds_read_b32 v56, v7 offset:32
	ds_read_b32 v57, v7 offset:164
	ds_read_b32 v58, v7 offset:296
	ds_read_b32 v59, v7 offset:428
	ds_read_b32 v60, v7 offset:560
	ds_read_b32 v61, v7 offset:692
	ds_read_b32 v62, v7 offset:824
	ds_read_b32 v63, v7 offset:956
	s_waitcnt lgkmcnt(0)
	v_cvt_pk_bf16_f32 v84, v56, v57
	v_cvt_pk_bf16_f32 v85, v58, v59
	v_cvt_pk_bf16_f32 v86, v60, v61
	v_cvt_pk_bf16_f32 v87, v62, v63
	global_store_dwordx4 v9, v[84:87], s[92:93]
	ds_read_b32 v64, v7 offset:64
	ds_read_b32 v65, v7 offset:196
	ds_read_b32 v66, v7 offset:328
	ds_read_b32 v67, v7 offset:460
	ds_read_b32 v68, v7 offset:592
	ds_read_b32 v69, v7 offset:724
	ds_read_b32 v70, v7 offset:856
	ds_read_b32 v71, v7 offset:988
	s_waitcnt lgkmcnt(0)
	v_cvt_pk_bf16_f32 v88, v64, v65
	v_cvt_pk_bf16_f32 v89, v66, v67
	v_cvt_pk_bf16_f32 v90, v68, v69
	v_cvt_pk_bf16_f32 v91, v70, v71
	global_store_dwordx4 v10, v[88:91], s[92:93]
	ds_read_b32 v72, v7 offset:96
	ds_read_b32 v73, v7 offset:228
	ds_read_b32 v74, v7 offset:360
	ds_read_b32 v75, v7 offset:492
	ds_read_b32 v76, v7 offset:624
	ds_read_b32 v77, v7 offset:756
	ds_read_b32 v78, v7 offset:888
	ds_read_b32 v79, v7 offset:1020
	s_waitcnt lgkmcnt(0)
	v_cvt_pk_bf16_f32 v92, v72, v73
	v_cvt_pk_bf16_f32 v93, v74, v75
	v_cvt_pk_bf16_f32 v94, v76, v77
	v_cvt_pk_bf16_f32 v95, v78, v79
	global_store_dwordx4 v11, v[92:95], s[92:93]
	s_add_i32 s85, s85, 0x1600
	s_branch .Lgconv_wgu_loop
